# P4 out-proj K-loop: third LDS stage in the unused gaps of the half-height tile layout, K-tiles DMA'd two ahead, per-tile wait vmcnt(6) instead of 0
# speedup vs baseline: 1.0042x; 1.0042x over previous
; #define G_BARRIER() { asm volatile("s_waitcnt vmcnt(0) lgkmcnt(0)" ::: "memory"); __builtin_amdgcn_s_barrier(); asm volatile("" ::: "memory"); }
;     ...
;         f32x16 acc[2][TB];
; #pragma unroll
;         for (int a = 0; a < 2; ++a)
; #pragma unroll
;             for (int b = 0; b < TB; ++b)
; #pragma unroll
;                 for (int i = 0; i < 16; ++i) acc[a][b][i] = 0.f;
;         G_BARRIER();
;         for (int kt = 0; kt < nk; ++kt) {
;             if (kt + 1 < nk) { G_DMA(kt + 1, (kt + 1) & 1); }
.LBB0_481:
	s_waitcnt vmcnt(0) lgkmcnt(0)
	s_barrier
	v_mov_b32_e32 v0, 0
	s_mov_b32 s18, s89
	s_mov_b32 s6, 0
	s_mov_b64 s[4:5], 0
	v_mov_b32_e32 v1, v0
	v_mov_b32_e32 v2, v0
	v_mov_b32_e32 v3, v0
	v_mov_b32_e32 v4, v0
	v_mov_b32_e32 v5, v0
	v_mov_b32_e32 v6, v0
	v_mov_b32_e32 v7, v0
	v_mov_b32_e32 v8, v0
	v_mov_b32_e32 v9, v0
	v_mov_b32_e32 v10, v0
	v_mov_b32_e32 v11, v0
	v_mov_b32_e32 v12, v0
	v_mov_b32_e32 v13, v0
	v_mov_b32_e32 v14, v0
	v_mov_b32_e32 v15, v0
	v_mov_b32_e32 v16, v0
	v_mov_b32_e32 v17, v0
	v_mov_b32_e32 v18, v0
	v_mov_b32_e32 v19, v0
	v_mov_b32_e32 v20, v0
	v_mov_b32_e32 v21, v0
	v_mov_b32_e32 v22, v0
	v_mov_b32_e32 v23, v0
	v_mov_b32_e32 v24, v0
	v_mov_b32_e32 v25, v0
	v_mov_b32_e32 v26, v0
	v_mov_b32_e32 v27, v0
	v_mov_b32_e32 v28, v0
	v_mov_b32_e32 v29, v0
	v_mov_b32_e32 v30, v0
	v_mov_b32_e32 v31, v0
	v_mov_b32_e32 v32, v0
	v_mov_b32_e32 v33, v0
	v_mov_b32_e32 v34, v0
	v_mov_b32_e32 v35, v0
	v_mov_b32_e32 v36, v0
	v_mov_b32_e32 v37, v0
	v_mov_b32_e32 v38, v0
	v_mov_b32_e32 v39, v0
	v_mov_b32_e32 v40, v0
	v_mov_b32_e32 v41, v0
	v_mov_b32_e32 v42, v0
	v_mov_b32_e32 v43, v0
	v_mov_b32_e32 v44, v0
	v_mov_b32_e32 v45, v0
	v_mov_b32_e32 v46, v0
	v_mov_b32_e32 v47, v0
	v_mov_b32_e32 v48, v0
	v_mov_b32_e32 v49, v0
	v_mov_b32_e32 v50, v0
	v_mov_b32_e32 v51, v0
	v_mov_b32_e32 v52, v0
	v_mov_b32_e32 v53, v0
	v_mov_b32_e32 v54, v0
	v_mov_b32_e32 v55, v0
	v_mov_b32_e32 v56, v0
	v_mov_b32_e32 v57, v0
	v_mov_b32_e32 v58, v0
	v_mov_b32_e32 v59, v0
	v_mov_b32_e32 v60, v0
	v_mov_b32_e32 v61, v0
	v_mov_b32_e32 v62, v0
	v_mov_b32_e32 v63, v0
	v_readfirstlane_b32 s76, v86
	v_readfirstlane_b32 s77, v87
	v_readfirstlane_b32 s78, v88
	v_readfirstlane_b32 s79, v89
	v_readfirstlane_b32 s32, v84
	s_nop 3
	s_sub_u32 s76, s76, s32
	s_subb_u32 s77, s77, 0
	s_add_u32 s76, s76, s4
	s_addc_u32 s77, s77, s5
	s_sub_u32 s78, s78, s32
	s_subb_u32 s79, s79, 0
	s_add_u32 s78, s78, s4
	s_addc_u32 s79, s79, s5
	v_add_u32_e32 v240, 0x80, v84
	v_add_u32_e32 v241, 0x20080, v84
	v_add_u32_e32 v242, 0x40080, v84
	v_add_u32_e32 v243, 0x60080, v84
	v_cmp_gt_u32_e32 vcc, 0x4000, v121
	v_mov_b32_e32 v171, 0x14000
	v_mov_b32_e32 v170, 0xc000
	v_cndmask_b32_e32 v170, v171, v170, vcc
	v_add3_u32 v170, v170, v121, v120
	v_add_u32_e32 v170, 16, v170
	s_mov_b32 s97, 0
	s_add_i32 s19, s16, 0x10000
	s_mov_b32 m0, s19
	s_nop 0
	global_load_lds_dwordx4 v240, s[76:77]
	s_add_i32 m0, s19, 0x8000
	s_nop 0
	global_load_lds_dwordx4 v240, s[78:79]
	s_add_i32 m0, s19, 0x2000
	s_nop 0
	global_load_lds_dwordx4 v241, s[76:77]
	s_add_i32 m0, s19, 0xa000
	s_nop 0
	global_load_lds_dwordx4 v241, s[78:79]
	s_add_i32 m0, s19, 0xc000
	s_nop 0
	global_load_lds_dwordx4 v242, s[78:79]
	s_add_i32 m0, s19, 0xe000
	s_nop 0
	global_load_lds_dwordx4 v243, s[78:79]
	s_add_u32 s76, s76, 0x80
	s_addc_u32 s77, s77, 0
	s_add_u32 s78, s78, 0x80
	s_addc_u32 s79, s79, 0
; #define MFMA(a, b, c) __builtin_amdgcn_mfma_f32_32x32x16_bf16((a), (b), (c), 0, 0, 0)
; #define G_BARRIER() { asm volatile("s_waitcnt vmcnt(0) lgkmcnt(0)" ::: "memory"); __builtin_amdgcn_s_barrier(); asm volatile("" ::: "memory"); }
;     ...
;         for (int kt = 0; kt < nk; ++kt) {
;             if (kt + 1 < nk) { G_DMA(kt + 1, (kt + 1) & 1); }
;             const unsigned char* sa = lds + (kt & 1) * 65536 + (wt * 32 * TB + r) * 128;
;             const unsigned char* sw = lds + (kt & 1) * 65536 + 32768 + (wf * 64 + r) * 128;
; #pragma unroll
;             for (int ks = 0; ks < 4; ++ks) {
;                 bf16x8 wfr[2], afr[TB];
; #pragma unroll
;                 for (int fb = 0; fb < 2; ++fb) wfr[fb] = *(const bf16x8*)(sw + fb * 4096 + koff[ks]);
; #pragma unroll
;                 for (int tb = 0; tb < TB; ++tb) afr[tb] = *(const bf16x8*)(sa + tb * 4096 + koff[ks]);
; #pragma unroll
;                 for (int fb = 0; fb < 2; ++fb)
; #pragma unroll
;                     for (int tb = 0; tb < TB; ++tb) acc[fb][tb] = MFMA(wfr[fb], afr[tb], acc[fb][tb]);
;             }
;             G_BARRIER();
;         }
.LBB0_482:
	s_add_i32 s7, s6, 0x10000
	s_lshl_b32 s98, s97, 16
	s_cmp_eq_u32 s97, 2
	s_cselect_b64 vcc, -1, 0
	s_cselect_b32 s99, 0x4000, s98
	s_add_i32 s99, s99, 16
	s_add_i32 s98, s98, 16
	v_add3_u32 v64, s99, v119, v120
	v_add3_u32 v85, s98, v121, v120
	v_cndmask_b32_e32 v85, v85, v170, vcc
	s_add_i32 s100, s97, -1
	s_cmp_eq_u32 s97, 0
	s_cselect_b32 s100, 2, s100
	s_lshl_b32 s101, s100, 16
	s_add_i32 s6, s101, 0x8000
	s_add_i32 s98, s101, 0xc000
	s_cmp_eq_u32 s100, 2
	s_cselect_b32 s19, 0x4000, s101
	s_cselect_b32 s6, 0x14000, s6
	s_cselect_b32 s98, 0x20000, s98
	s_add_i32 s19, s16, s19
	s_add_i32 s6, s16, s6
	s_add_i32 s98, s16, s98
	s_add_i32 s97, s97, 1
	s_cmp_eq_u32 s97, 3
	s_cselect_b32 s97, 0, s97
	s_mov_b32 m0, s19
	s_nop 0
	global_load_lds_dwordx4 v240, s[76:77]
	s_mov_b32 m0, s6
	s_nop 0
	global_load_lds_dwordx4 v240, s[78:79]
	s_add_i32 m0, s19, 0x2000
	s_mov_b64 s[90:91], 0x40080
	s_nop 0
	global_load_lds_dwordx4 v241, s[76:77]
	s_add_i32 m0, s6, 0x2000
	s_mov_b64 s[92:93], 0x60080
	s_nop 0
	global_load_lds_dwordx4 v241, s[78:79]
	s_mov_b32 m0, s98
	s_nop 0
	global_load_lds_dwordx4 v242, s[78:79]
	s_add_i32 m0, s98, 0x2000
	v_add_u32_e32 v102, v85, v114
	s_nop 0
	global_load_lds_dwordx4 v243, s[78:79]
	s_add_u32 s76, s76, 0x80
	s_addc_u32 s77, s77, 0
	s_add_u32 s78, s78, 0x80
	s_addc_u32 s79, s79, 0
	v_add_u32_e32 v103, v64, v114
	ds_read_b128 v[90:93], v102 offset:32768
	ds_read_b128 v[94:97], v103
	ds_read_b128 v[98:101], v103 offset:4096
	ds_read_b128 v[102:105], v102 offset:36864
	v_add_u32_e32 v106, v85, v115
	v_add_u32_e32 v107, v64, v115
	ds_read_b128 v[152:155], v106 offset:32768
	ds_read_b128 v[156:159], v107
	ds_read_b128 v[160:163], v107 offset:4096
	ds_read_b128 v[164:167], v106 offset:36864
	s_waitcnt lgkmcnt(4)
	v_mfma_f32_32x32x16_bf16 v[48:63], v[90:93], v[94:97], v[48:63]
	s_add_u32 s4, s4, 0x80
	s_addc_u32 s5, s5, 0
	s_cmpk_eq_i32 s4, 0x780
	s_mov_b32 s6, s7
	v_mfma_f32_32x32x16_bf16 v[32:47], v[90:93], v[98:101], v[32:47]
	v_mfma_f32_32x32x16_bf16 v[16:31], v[102:105], v[94:97], v[16:31]
	v_mfma_f32_32x32x16_bf16 v[0:15], v[102:105], v[98:101], v[0:15]
	v_add_u32_e32 v106, v85, v116
	v_add_u32_e32 v107, v64, v116
	ds_read_b128 v[90:93], v106 offset:32768
	ds_read_b128 v[94:97], v107
	ds_read_b128 v[98:101], v107 offset:4096
	ds_read_b128 v[102:105], v106 offset:36864
	s_waitcnt lgkmcnt(4)
	v_mfma_f32_32x32x16_bf16 v[48:63], v[152:155], v[156:159], v[48:63]
	v_mfma_f32_32x32x16_bf16 v[32:47], v[152:155], v[160:163], v[32:47]
	v_mfma_f32_32x32x16_bf16 v[16:31], v[164:167], v[156:159], v[16:31]
	v_mfma_f32_32x32x16_bf16 v[0:15], v[164:167], v[160:163], v[0:15]
	v_add_u32_e32 v85, v85, v117
	v_add_u32_e32 v64, v64, v117
	ds_read_b128 v[152:155], v85 offset:32768
	ds_read_b128 v[156:159], v64
	ds_read_b128 v[160:163], v64 offset:4096
	ds_read_b128 v[164:167], v85 offset:36864
	s_waitcnt lgkmcnt(4)
	v_mfma_f32_32x32x16_bf16 v[48:63], v[90:93], v[94:97], v[48:63]
	v_mfma_f32_32x32x16_bf16 v[32:47], v[90:93], v[98:101], v[32:47]
	v_mfma_f32_32x32x16_bf16 v[16:31], v[102:105], v[94:97], v[16:31]
	v_mfma_f32_32x32x16_bf16 v[0:15], v[102:105], v[98:101], v[0:15]
	s_waitcnt vmcnt(6) lgkmcnt(0)
	s_barrier
	v_mfma_f32_32x32x16_bf16 v[48:63], v[152:155], v[156:159], v[48:63]
	v_mfma_f32_32x32x16_bf16 v[32:47], v[152:155], v[160:163], v[32:47]
	v_mfma_f32_32x32x16_bf16 v[16:31], v[164:167], v[156:159], v[16:31]
	v_mfma_f32_32x32x16_bf16 v[0:15], v[164:167], v[160:163], v[0:15]
	s_cbranch_scc0 .LBB0_482
	v_add_u32_e32 v168, 0xffff0000, v124
	v_add_u32_e32 v169, 0xffff0000, v125
	v_add_u32_e32 v64, v169, v114
	ds_read_b128 v[90:93], v64
	v_add_u32_e32 v85, v168, v114
	ds_read_b128 v[94:97], v85
	ds_read_b128 v[98:101], v85 offset:4096
	ds_read_b128 v[102:105], v64 offset:4096
	v_add_u32_e32 v64, v169, v115
	v_add_u32_e32 v85, v168, v115
	s_waitcnt lgkmcnt(0)
	v_mfma_f32_32x32x16_bf16 v[16:31], v[102:105], v[94:97], v[16:31]
	s_add_i32 s89, s18, s25
	s_cmp_ge_i32 s89, s26
	s_cselect_b64 s[6:7], -1, 0
	s_cmp_lt_i32 s89, s26
	v_mfma_f32_32x32x16_bf16 v[48:63], v[90:93], v[94:97], v[48:63]
	v_mfma_f32_32x32x16_bf16 v[32:47], v[90:93], v[98:101], v[32:47]
	ds_read_b128 v[90:93], v64
	v_mfma_f32_32x32x16_bf16 v[0:15], v[102:105], v[98:101], v[0:15]
	ds_read_b128 v[94:97], v85
	ds_read_b128 v[98:101], v85 offset:4096
	ds_read_b128 v[102:105], v64 offset:4096
	v_add_u32_e32 v64, v169, v116
	v_add_u32_e32 v85, v168, v116
	s_waitcnt lgkmcnt(0)
	v_mfma_f32_32x32x16_bf16 v[48:63], v[90:93], v[94:97], v[48:63]
	v_mfma_f32_32x32x16_bf16 v[32:47], v[90:93], v[98:101], v[32:47]
	ds_read_b128 v[90:93], v64
	v_mfma_f32_32x32x16_bf16 v[16:31], v[102:105], v[94:97], v[16:31]
	v_mfma_f32_32x32x16_bf16 v[0:15], v[102:105], v[98:101], v[0:15]
	ds_read_b128 v[94:97], v85
	ds_read_b128 v[98:101], v85 offset:4096
	ds_read_b128 v[102:105], v64 offset:4096
	v_add_u32_e32 v64, v169, v117
	v_add_u32_e32 v85, v168, v117
	s_waitcnt lgkmcnt(0)
	v_mfma_f32_32x32x16_bf16 v[48:63], v[90:93], v[94:97], v[48:63]
	v_mfma_f32_32x32x16_bf16 v[32:47], v[90:93], v[98:101], v[32:47]
	ds_read_b128 v[90:93], v64
	v_mfma_f32_32x32x16_bf16 v[16:31], v[102:105], v[94:97], v[16:31]
	v_mfma_f32_32x32x16_bf16 v[0:15], v[102:105], v[98:101], v[0:15]
	ds_read_b128 v[94:97], v85
	ds_read_b128 v[98:101], v85 offset:4096
	ds_read_b128 v[102:105], v64 offset:4096
	s_waitcnt vmcnt(0) lgkmcnt(0)
	s_barrier
	s_waitcnt lgkmcnt(0)
	v_mfma_f32_32x32x16_bf16 v[48:63], v[90:93], v[94:97], v[48:63]
	v_mfma_f32_32x32x16_bf16 v[32:47], v[90:93], v[98:101], v[32:47]
	v_mfma_f32_32x32x16_bf16 v[16:31], v[102:105], v[94:97], v[16:31]
	v_mfma_f32_32x32x16_bf16 v[0:15], v[102:105], v[98:101], v[0:15]
	s_cbranch_scc0 .LBB0_485
	s_ashr_i32 s4, s89, 31
	s_lshr_b32 s4, s4, 30
	s_add_i32 s19, s89, s4
	s_ashr_i32 s4, s19, 2
	s_lshl_b32 s4, s4, s22
	s_add_i32 s4, s4, s24
	s_ashr_i32 s5, s4, 31
	s_lshl_b64 s[4:5], s[4:5], 18
	s_add_u32 s4, s1, s4
	s_addc_u32 s5, s3, s5
	s_and_b32 s19, s19, -4
	s_sub_i32 s90, s89, s19
	s_ashr_i32 s91, s90, 31
	s_lshl_b64 s[90:91], s[90:91], 19
	s_mov_b32 m0, s16
	v_mov_b32_e32 v85, v65
	s_add_u32 s90, s20, s90
	v_lshl_add_u64 v[86:87], s[4:5], 0, v[84:85]
	s_addc_u32 s91, s21, s91
	global_load_lds_dwordx4 v84, s[4:5]
	s_mov_b32 m0, s84
	v_lshl_add_u64 v[88:89], s[90:91], 0, v[84:85]
	global_load_lds_dwordx4 v84, s[90:91]
	v_lshl_add_u64 v[90:91], v[86:87], 0, s[38:39]
	s_mov_b32 m0, s85
	s_nop 0
	global_load_lds_dwordx4 v[90:91], off
	v_lshl_add_u64 v[90:91], v[88:89], 0, s[38:39]
	s_mov_b32 m0, s86
	s_nop 0
	global_load_lds_dwordx4 v[90:91], off
	v_lshl_add_u64 v[90:91], v[88:89], 0, s[42:43]
	s_mov_b32 m0, s87
	s_nop 0
	global_load_lds_dwordx4 v[90:91], off
	v_lshl_add_u64 v[90:91], v[88:89], 0, s[44:45]
	s_mov_b32 m0, s88
	s_nop 0
	global_load_lds_dwordx4 v[90:91], off
